# attention item loops prefetch (cache-warm) the SiLU-gate rows their epilogue reads a few tiles ahead (plain loads in A/B, LDS-DMA to scratch LDS in C): z is written write-through so those rows are not
# speedup vs baseline: 1.1066x; 1.0093x over previous
.Lb_nodma:
.Lb_nobar:
	s_add_i32 s18, s25, 0xffff4000
	s_and_b32 s24, s18, 0xc000
	s_sub_i32 s18, s94, s42
	s_cmp_eq_u32 s18, 0xffffff80
	s_cbranch_scc1 .Lb_em2
	s_cmp_eq_u32 s18, 0x80
	s_cbranch_scc1 .Lb_ep2
	s_cmp_lg_u32 s18, 0
	s_cbranch_scc1 .Lb_nopf
	v_add_u32_e32 v216, s77, v221
	v_cmp_gt_u32_e32 vcc, 0x100, v216
	v_mov_b32_e32 v248, s43
	v_mov_b32_e32 v249, s21
	v_cndmask_b32_e32 v248, v248, v249, vcc
	v_mov_b32_e32 v249, s20
	v_mov_b32_e32 v252, s9
	v_cndmask_b32_e32 v249, v249, v252, vcc
	v_and_b32_e32 v216, 0xc0, v216
	v_lshl_or_b32 v216, v248, 8, v216
	v_add_u32_e32 v216, s45, v216
	v_and_or_b32 v216, v221, 31, v216
	v_lshlrev_b32_e32 v248, 7, v249
	v_mov_b32_e32 v249, 0
	v_mov_b64_e32 v[214:215], s[74:75]
	v_mad_u64_u32 v[214:215], s[22:23], v216, s4, v[214:215]
	v_lshl_add_u64 v[214:215], v[214:215], 0, v[248:249]
	s_mov_b64 s[22:23], 0x4400d00
	v_lshl_add_u64 v[214:215], v[214:215], 0, s[22:23]
	global_load_dword v252, v[214:215], off
	global_load_dword v252, v[214:215], off offset:64
	s_mov_b64 s[22:23], 0x29800
	v_lshl_add_u64 v[214:215], v[214:215], 0, s[22:23]
	global_load_dword v252, v[214:215], off
	global_load_dword v252, v[214:215], off offset:64
.Lb_nopf:
	s_add_i32 s18, s18, 64
	s_cmp_gt_u32 s18, 0x80
	s_cbranch_scc1 .Lb_next

.La_loop:
	s_cmp_lg_u32 s28, 7
	s_cbranch_scc1 .La_nopf
	v_add_u32_e32 v136, s77, v221
	v_cmp_gt_u32_e32 vcc, 0x100, v136
	v_mov_b32_e32 v137, s43
	v_mov_b32_e32 v138, s21
	v_cndmask_b32_e32 v137, v137, v138, vcc
	v_mov_b32_e32 v138, s20
	v_mov_b32_e32 v139, s9
	v_cndmask_b32_e32 v138, v138, v139, vcc
	v_and_b32_e32 v136, 0xc0, v136
	v_lshl_or_b32 v136, v137, 8, v136
	v_add_u32_e32 v136, s45, v136
	v_and_or_b32 v136, v221, 31, v136
	v_lshlrev_b32_e32 v138, 7, v138
	v_mov_b32_e32 v139, 0
	v_mov_b64_e32 v[140:141], s[74:75]
	v_mad_u64_u32 v[140:141], s[18:19], v136, s4, v[140:141]
	v_lshl_add_u64 v[140:141], v[140:141], 0, v[138:139]
	s_mov_b64 s[18:19], 0x4400600
	v_lshl_add_u64 v[140:141], v[140:141], 0, s[18:19]
	global_load_dword v142, v[140:141], off
	global_load_dword v142, v[140:141], off offset:64
	s_mov_b64 s[18:19], 0x29800
	v_lshl_add_u64 v[140:141], v[140:141], 0, s[18:19]
	global_load_dword v142, v[140:141], off
	global_load_dword v142, v[140:141], off offset:64

.Lc_bar:
	s_barrier
	s_cmp_lg_u32 s20, 30
	s_cbranch_scc1 .Lc_nopf
	v_add_u32_e32 v248, s77, v221
	v_cmp_gt_u32_e32 vcc, 0x100, v248
	v_mov_b32_e32 v249, s30
	v_mov_b32_e32 v250, s28
	v_cndmask_b32_e32 v249, v249, v250, vcc
	v_and_b32_e32 v248, 0xc0, v248
	v_and_b32_e32 v250, 31, v221
	v_lshl_or_b32 v248, v249, 8, v248
	v_or3_b32 v248, v248, v250, s40
	v_mov_b64_e32 v[212:213], s[74:75]
	v_mad_u64_u32 v[212:213], s[0:1], v248, s4, v[212:213]
	v_mov_b32_e32 v249, 0x14c0
	v_mad_i32_i24 v213, s41, v249, v213
	s_lshl_b32 s18, s31, 1
	s_mov_b32 s19, 0
	v_lshl_add_u64 v[212:213], v[212:213], 0, s[18:19]
	s_mov_b64 s[18:19], 0x44012c0
	v_lshl_add_u64 v[212:213], v[212:213], 0, s[18:19]
	s_mov_b32 m0, 0x18000
	s_nop 0
	global_load_lds_dword v[212:213], off
	global_load_lds_dword v[212:213], off offset:64
	s_mov_b64 s[18:19], 0x29800
	v_lshl_add_u64 v[212:213], v[212:213], 0, s[18:19]
	global_load_lds_dword v[212:213], off
	global_load_lds_dword v[212:213], off offset:64
.Lc_nopf:
	s_cmp_gt_u32 s20, 29
	s_cbranch_scc1 .Lc_nodma
	s_mul_i32 s0, s8, 0x5000
	v_add_u32_e32 v212, s0, v217
	v_add_u32_e32 v213, 0x2000, v212
	v_readfirstlane_b32 s0, v212
	s_mov_b32 m0, s0
	v_readfirstlane_b32 s0, v213
	global_load_lds_dwordx4 v[208:209], off
	s_mov_b32 m0, s0
	s_nop 0
	global_load_lds_dwordx4 v[204:205], off
	s_and_saveexec_b64 s[0:1], s[36:37]
	s_cbranch_execz .Lc_nokr
	v_add_u32_e32 v212, 0x4000, v212
	s_nop 0
	v_readfirstlane_b32 s18, v212
	s_mov_b32 m0, s18
	s_nop 0
	global_load_lds_dwordx4 v[206:207], off
